# hoist independent prologue loads of forgetting-attention units above the first barrier (one memory round trip instead of five)
# baseline (speedup 1.0000x reference)
; #define PG8_STAGE(bufoff, gbase, voff) do { _Pragma("unroll") for (int _i = 0; _i < 2; ++_i) \
;         __builtin_amdgcn_global_load_lds((const unsigned*)((const char*)(gbase) + (voff)[_i]), (PG8_LAS unsigned*)(lds + (bufoff) + ldsw + _i * 8192), 16, 0, 0); } while (0)
; #define PG8_LDA(dst, b, h) do { _Pragma("unroll") for (int m = 0; m < 4; ++m) _Pragma("unroll") for (int k = 0; k < 2; ++k) dst[m][k] = *(const PG8_LAS bf16x8*)(lds + PG8_SA(b, h) + aoff + m * 2048 + k * 1024); } while (0)
; #define PG8_LDB(dst, b, h) do { _Pragma("unroll") for (int n = 0; n < 2; ++n) _Pragma("unroll") for (int k = 0; k < 2; ++k) dst[n][k] = *(const PG8_LAS bf16x8*)(lds + PG8_SB(b, h) + boff + n * 2048 + k * 1024); } while (0)
; #define PG8_MMA(ai, bj, At, Bt) do { __builtin_amdgcn_s_setprio(1); _Pragma("unroll") for (int m = 0; m < 4; ++m) _Pragma("unroll") for (int n = 0; n < 2; ++n) _Pragma("unroll") for (int k = 0; k < 2; ++k) \
;         acc[ai][bj][m][n] = __builtin_amdgcn_mfma_f32_16x16x32_bf16(Bt[n][k], At[m][k], acc[ai][bj][m][n], 0, 0, 0); __builtin_amdgcn_s_setprio(0); } while (0)
; #define PG8_WAIT_V(n) asm volatile("s_waitcnt vmcnt(" #n ")" ::: "memory")
; #define PG8_WAIT_L(n) asm volatile("s_waitcnt lgkmcnt(" #n ")" ::: "memory")
; #define PG8_BAR __builtin_amdgcn_s_barrier()
; #define PG8_SCHED __builtin_amdgcn_sched_barrier(0)
; template <class Epi, class Sched, bool ALIGN_EPI = false, bool SP2 = false>
; __device__ __forceinline__ void gemm_phase(PG8_LAS unsigned char* lds, const Gemm g, const Sched& S, const Epi& E) {
;     ...
;             PG8_LDB(B0, 0, 0); PG8_LDB(B1, 0, 1); PG8_SCHED; PG8_LDA(At, 0, 0); PG8_STAGE(PG8_SA(1, 1), a1 + hstep, voffA);
;             PG8_WAIT_V(8); PG8_WAIT_L(0); PG8_BAR; PG8_MMA(0, 0, At, B0); PG8_MMA(0, 1, At, B1); PG8_BAR; PG8_SCHED;
;             if (full) PG8_LDA(At, 0, 1); PG8_STAGE(PG8_SB(0, 0), b2, voffB); PG8_STAGE(PG8_SB(0, 1), b2 + hstep, voffB); PG8_STAGE(PG8_SA(0, 0), a2, voffA);
.LBB0_292:
	v_add_u32_e32 v0, 0x10000, v223
	ds_read_b128 v[148:151], v0
	ds_read_b128 v[152:155], v0 offset:1024
	ds_read_b128 v[156:159], v0 offset:2048
	ds_read_b128 v[160:163], v0 offset:3072
	v_add_u32_e32 v0, 0x14000, v223
	ds_read_b128 v[132:135], v0
	ds_read_b128 v[136:139], v0 offset:1024
	ds_read_b128 v[140:143], v0 offset:2048
	ds_read_b128 v[144:147], v0 offset:3072
	v_lshl_add_u64 v[2:3], s[36:37], 0, v[204:205]
	s_add_i32 m0, s31, 0xc000
	ds_read_b128 v[176:179], v224
	ds_read_b128 v[192:195], v224 offset:1024
	ds_read_b128 v[172:175], v224 offset:2048
	ds_read_b128 v[188:191], v224 offset:3072
	ds_read_b128 v[168:171], v224 offset:4096
	ds_read_b128 v[184:187], v224 offset:5120
	ds_read_b128 v[164:167], v224 offset:6144
	ds_read_b128 v[180:183], v224 offset:7168
	global_load_lds_dwordx4 v[2:3], off
	v_lshl_add_u64 v[2:3], s[36:37], 0, v[206:207]
	s_add_i32 m0, s31, 0xe000
	s_nop 0
	global_load_lds_dwordx4 v[2:3], off
	s_waitcnt vmcnt(8)
	s_waitcnt lgkmcnt(0)
	s_barrier
	s_setprio 1
	s_waitcnt lgkmcnt(0)
	v_mfma_f32_16x16x32_bf16 v[128:131], v[148:151], v[176:179], v[128:131]
	v_mfma_f32_16x16x32_bf16 v[124:127], v[156:159], v[176:179], v[124:127]
	v_mfma_f32_16x16x32_bf16 v[112:115], v[148:151], v[172:175], v[112:115]
	v_mfma_f32_16x16x32_bf16 v[108:111], v[156:159], v[172:175], v[108:111]
	v_mfma_f32_16x16x32_bf16 v[96:99], v[148:151], v[168:171], v[96:99]
	v_mfma_f32_16x16x32_bf16 v[92:95], v[156:159], v[168:171], v[92:95]
	v_mfma_f32_16x16x32_bf16 v[80:83], v[148:151], v[164:167], v[80:83]
	v_mfma_f32_16x16x32_bf16 v[76:79], v[156:159], v[164:167], v[76:79]
	v_mfma_f32_16x16x32_bf16 v[128:131], v[152:155], v[192:195], v[128:131]
	v_mfma_f32_16x16x32_bf16 v[124:127], v[160:163], v[192:195], v[124:127]
	v_mfma_f32_16x16x32_bf16 v[112:115], v[152:155], v[188:191], v[112:115]
	v_mfma_f32_16x16x32_bf16 v[108:111], v[160:163], v[188:191], v[108:111]
	v_mfma_f32_16x16x32_bf16 v[96:99], v[152:155], v[184:187], v[96:99]
	v_mfma_f32_16x16x32_bf16 v[92:95], v[160:163], v[184:187], v[92:95]
	v_mfma_f32_16x16x32_bf16 v[80:83], v[152:155], v[180:183], v[80:83]
	v_mfma_f32_16x16x32_bf16 v[76:79], v[160:163], v[180:183], v[76:79]
	s_setprio 0
	s_setprio 1
	v_mfma_f32_16x16x32_bf16 v[120:123], v[132:135], v[176:179], v[120:123]
	v_mfma_f32_16x16x32_bf16 v[116:119], v[140:143], v[176:179], v[116:119]
	v_mfma_f32_16x16x32_bf16 v[104:107], v[132:135], v[172:175], v[104:107]
	v_mfma_f32_16x16x32_bf16 v[100:103], v[140:143], v[172:175], v[100:103]
	v_mfma_f32_16x16x32_bf16 v[88:91], v[132:135], v[168:171], v[88:91]
	v_mfma_f32_16x16x32_bf16 v[84:87], v[140:143], v[168:171], v[84:87]
	v_mfma_f32_16x16x32_bf16 v[72:75], v[132:135], v[164:167], v[72:75]
	v_mfma_f32_16x16x32_bf16 v[68:71], v[140:143], v[164:167], v[68:71]
	v_mfma_f32_16x16x32_bf16 v[120:123], v[136:139], v[192:195], v[120:123]
	v_mfma_f32_16x16x32_bf16 v[116:119], v[144:147], v[192:195], v[116:119]
	v_mfma_f32_16x16x32_bf16 v[104:107], v[136:139], v[188:191], v[104:107]
	v_mfma_f32_16x16x32_bf16 v[100:103], v[144:147], v[188:191], v[100:103]
	v_mfma_f32_16x16x32_bf16 v[88:91], v[136:139], v[184:187], v[88:91]
	v_mfma_f32_16x16x32_bf16 v[84:87], v[144:147], v[184:187], v[84:87]
	v_mfma_f32_16x16x32_bf16 v[72:75], v[136:139], v[180:183], v[72:75]
	v_mfma_f32_16x16x32_bf16 v[68:71], v[144:147], v[180:183], v[68:71]
	s_setprio 0
	s_barrier
	v_cndmask_b32_e64 v0, 0, 1, s[34:35]
	v_cmp_ne_u32_e64 s[4:5], 1, v0
	s_andn2_b64 vcc, exec, s[34:35]
	s_cbranch_vccnz .LBB0_294
	ds_read_b128 v[176:179], v224 offset:16384
	ds_read_b128 v[192:195], v224 offset:17408
	ds_read_b128 v[172:175], v224 offset:18432
	ds_read_b128 v[188:191], v224 offset:19456
	ds_read_b128 v[168:171], v224 offset:20480
	ds_read_b128 v[184:187], v224 offset:21504
	ds_read_b128 v[164:167], v224 offset:22528
	ds_read_b128 v[180:183], v224 offset:23552

; #define PG8_STAGE(bufoff, gbase, voff) do { _Pragma("unroll") for (int _i = 0; _i < 2; ++_i) \
;         __builtin_amdgcn_global_load_lds((const unsigned*)((const char*)(gbase) + (voff)[_i]), (PG8_LAS unsigned*)(lds + (bufoff) + ldsw + _i * 8192), 16, 0, 0); } while (0)
; #define PG8_LDA(dst, b, h) do { _Pragma("unroll") for (int m = 0; m < 4; ++m) _Pragma("unroll") for (int k = 0; k < 2; ++k) dst[m][k] = *(const PG8_LAS bf16x8*)(lds + PG8_SA(b, h) + aoff + m * 2048 + k * 1024); } while (0)
; #define PG8_LDB(dst, b, h) do { _Pragma("unroll") for (int n = 0; n < 2; ++n) _Pragma("unroll") for (int k = 0; k < 2; ++k) dst[n][k] = *(const PG8_LAS bf16x8*)(lds + PG8_SB(b, h) + boff + n * 2048 + k * 1024); } while (0)
; #define PG8_MMA(ai, bj, At, Bt) do { __builtin_amdgcn_s_setprio(1); _Pragma("unroll") for (int m = 0; m < 4; ++m) _Pragma("unroll") for (int n = 0; n < 2; ++n) _Pragma("unroll") for (int k = 0; k < 2; ++k) \
;         acc[ai][bj][m][n] = __builtin_amdgcn_mfma_f32_16x16x32_bf16(Bt[n][k], At[m][k], acc[ai][bj][m][n], 0, 0, 0); __builtin_amdgcn_s_setprio(0); } while (0)
; #define PG8_WAIT_V(n) asm volatile("s_waitcnt vmcnt(" #n ")" ::: "memory")
; #define PG8_WAIT_L(n) asm volatile("s_waitcnt lgkmcnt(" #n ")" ::: "memory")
; #define PG8_BAR __builtin_amdgcn_s_barrier()
; #define PG8_SCHED __builtin_amdgcn_sched_barrier(0)
; template <class Epi, class Sched, bool ALIGN_EPI = false, bool SP2 = false>
; __device__ __forceinline__ void gemm_phase(PG8_LAS unsigned char* lds, const Gemm g, const Sched& S, const Epi& E) {
;     ...
;             PG8_LDB(B0, 1, 0); PG8_LDB(B1, 1, 1); PG8_SCHED; PG8_LDA(At, 1, 0); PG8_STAGE(PG8_SA(0, 1), a2 + hstep, voffA);
;             PG8_WAIT_V(8); PG8_WAIT_L(0); PG8_BAR; PG8_MMA(0, 0, At, B0); PG8_MMA(0, 1, At, B1); PG8_BAR; PG8_SCHED;
;             if (full) PG8_LDA(At, 1, 1); PG8_STAGE(PG8_SB(1, 0), b3, voffB); PG8_STAGE(PG8_SB(1, 1), b3 + hstep, voffB); PG8_STAGE(PG8_SA(1, 0), a3, voffA);
.LBB0_296:
	s_barrier
	v_add_u32_e32 v0, 0x18000, v223
	ds_read_b128 v[148:151], v0
	ds_read_b128 v[152:155], v0 offset:1024
	ds_read_b128 v[156:159], v0 offset:2048
	ds_read_b128 v[160:163], v0 offset:3072
	v_add_u32_e32 v0, 0x1c000, v223
	ds_read_b128 v[132:135], v0
	ds_read_b128 v[136:139], v0 offset:1024
	ds_read_b128 v[140:143], v0 offset:2048
	ds_read_b128 v[144:147], v0 offset:3072
	s_add_u32 s42, s42, 0x40000
	s_addc_u32 s43, s43, 0
	s_mov_b32 m0, s59
	v_lshl_add_u64 v[212:213], s[42:43], 0, v[196:197]
	ds_read_b128 v[176:179], v224 offset:32768
	ds_read_b128 v[192:195], v224 offset:33792
	ds_read_b128 v[172:175], v224 offset:34816
	ds_read_b128 v[188:191], v224 offset:35840
	ds_read_b128 v[168:171], v224 offset:36864
	ds_read_b128 v[184:187], v224 offset:37888
	ds_read_b128 v[164:167], v224 offset:38912
	ds_read_b128 v[180:183], v224 offset:39936
	global_load_lds_dwordx4 v[212:213], off
	v_lshl_add_u64 v[212:213], s[42:43], 0, v[200:201]
	s_mov_b32 m0, s60
	s_nop 0
	global_load_lds_dwordx4 v[212:213], off
	s_waitcnt vmcnt(8)
	s_waitcnt lgkmcnt(0)
	s_barrier
	s_setprio 1
	s_waitcnt lgkmcnt(0)
	v_mfma_f32_16x16x32_bf16 v[128:131], v[148:151], v[176:179], v[128:131]
	v_mfma_f32_16x16x32_bf16 v[124:127], v[156:159], v[176:179], v[124:127]
	v_mfma_f32_16x16x32_bf16 v[112:115], v[148:151], v[172:175], v[112:115]
	v_mfma_f32_16x16x32_bf16 v[108:111], v[156:159], v[172:175], v[108:111]
	v_mfma_f32_16x16x32_bf16 v[96:99], v[148:151], v[168:171], v[96:99]
	v_mfma_f32_16x16x32_bf16 v[92:95], v[156:159], v[168:171], v[92:95]
	v_mfma_f32_16x16x32_bf16 v[80:83], v[148:151], v[164:167], v[80:83]
	v_mfma_f32_16x16x32_bf16 v[76:79], v[156:159], v[164:167], v[76:79]
	v_mfma_f32_16x16x32_bf16 v[128:131], v[152:155], v[192:195], v[128:131]
	v_mfma_f32_16x16x32_bf16 v[124:127], v[160:163], v[192:195], v[124:127]
	v_mfma_f32_16x16x32_bf16 v[112:115], v[152:155], v[188:191], v[112:115]
	v_mfma_f32_16x16x32_bf16 v[108:111], v[160:163], v[188:191], v[108:111]
	v_mfma_f32_16x16x32_bf16 v[96:99], v[152:155], v[184:187], v[96:99]
	v_mfma_f32_16x16x32_bf16 v[92:95], v[160:163], v[184:187], v[92:95]
	v_mfma_f32_16x16x32_bf16 v[80:83], v[152:155], v[180:183], v[80:83]
	v_mfma_f32_16x16x32_bf16 v[76:79], v[160:163], v[180:183], v[76:79]
	s_setprio 0
	s_setprio 1
	v_mfma_f32_16x16x32_bf16 v[120:123], v[132:135], v[176:179], v[120:123]
	v_mfma_f32_16x16x32_bf16 v[116:119], v[140:143], v[176:179], v[116:119]
	v_mfma_f32_16x16x32_bf16 v[104:107], v[132:135], v[172:175], v[104:107]
	v_mfma_f32_16x16x32_bf16 v[100:103], v[140:143], v[172:175], v[100:103]
	v_mfma_f32_16x16x32_bf16 v[88:91], v[132:135], v[168:171], v[88:91]
	v_mfma_f32_16x16x32_bf16 v[84:87], v[140:143], v[168:171], v[84:87]
	v_mfma_f32_16x16x32_bf16 v[72:75], v[132:135], v[164:167], v[72:75]
	v_mfma_f32_16x16x32_bf16 v[68:71], v[140:143], v[164:167], v[68:71]
	v_mfma_f32_16x16x32_bf16 v[120:123], v[136:139], v[192:195], v[120:123]
	v_mfma_f32_16x16x32_bf16 v[116:119], v[144:147], v[192:195], v[116:119]
	v_mfma_f32_16x16x32_bf16 v[104:107], v[136:139], v[188:191], v[104:107]
	v_mfma_f32_16x16x32_bf16 v[100:103], v[144:147], v[188:191], v[100:103]
	v_mfma_f32_16x16x32_bf16 v[88:91], v[136:139], v[184:187], v[88:91]
	v_mfma_f32_16x16x32_bf16 v[84:87], v[144:147], v[184:187], v[84:87]
	v_mfma_f32_16x16x32_bf16 v[72:75], v[136:139], v[180:183], v[72:75]
	v_mfma_f32_16x16x32_bf16 v[68:71], v[144:147], v[180:183], v[68:71]
	s_setprio 0
	s_barrier
	s_and_b64 vcc, exec, s[4:5]
	s_cbranch_vccnz .LBB0_298
	ds_read_b128 v[176:179], v224 offset:49152
	ds_read_b128 v[192:195], v224 offset:50176
	ds_read_b128 v[172:175], v224 offset:51200
	ds_read_b128 v[188:191], v224 offset:52224
	ds_read_b128 v[168:171], v224 offset:53248
	ds_read_b128 v[184:187], v224 offset:54272
	ds_read_b128 v[164:167], v224 offset:55296
	ds_read_b128 v[180:183], v224 offset:56320

; #define PG8_STAGE(bufoff, gbase, voff) do { _Pragma("unroll") for (int _i = 0; _i < 2; ++_i) \
;         __builtin_amdgcn_global_load_lds((const unsigned*)((const char*)(gbase) + (voff)[_i]), (PG8_LAS unsigned*)(lds + (bufoff) + ldsw + _i * 8192), 16, 0, 0); } while (0)
; #define PG8_LDA(dst, b, h) do { _Pragma("unroll") for (int m = 0; m < 4; ++m) _Pragma("unroll") for (int k = 0; k < 2; ++k) dst[m][k] = *(const PG8_LAS bf16x8*)(lds + PG8_SA(b, h) + aoff + m * 2048 + k * 1024); } while (0)
; #define PG8_LDB(dst, b, h) do { _Pragma("unroll") for (int n = 0; n < 2; ++n) _Pragma("unroll") for (int k = 0; k < 2; ++k) dst[n][k] = *(const PG8_LAS bf16x8*)(lds + PG8_SB(b, h) + boff + n * 2048 + k * 1024); } while (0)
; #define PG8_MMA(ai, bj, At, Bt) do { __builtin_amdgcn_s_setprio(1); _Pragma("unroll") for (int m = 0; m < 4; ++m) _Pragma("unroll") for (int n = 0; n < 2; ++n) _Pragma("unroll") for (int k = 0; k < 2; ++k) \
;         acc[ai][bj][m][n] = __builtin_amdgcn_mfma_f32_16x16x32_bf16(Bt[n][k], At[m][k], acc[ai][bj][m][n], 0, 0, 0); __builtin_amdgcn_s_setprio(0); } while (0)
; #define PG8_WAIT_V(n) asm volatile("s_waitcnt vmcnt(" #n ")" ::: "memory")
; #define PG8_WAIT_L(n) asm volatile("s_waitcnt lgkmcnt(" #n ")" ::: "memory")
; #define PG8_BAR __builtin_amdgcn_s_barrier()
; #define PG8_SCHED __builtin_amdgcn_sched_barrier(0)
; template <class Epi, class Sched, bool ALIGN_EPI = false, bool SP2 = false>
; __device__ __forceinline__ void gemm_phase(PG8_LAS unsigned char* lds, const Gemm g, const Sched& S, const Epi& E) {
;     ...
;             PG8_LDB(B0, 0, 0); PG8_LDB(B1, 0, 1); PG8_SCHED; PG8_LDA(At, 0, 0); PG8_STAGE(PG8_SA(1, 1), a1 + hstep, voffA);
;             PG8_WAIT_V(8); PG8_WAIT_L(0); PG8_BAR; PG8_MMA(0, 0, At, B0); PG8_MMA(0, 1, At, B1); PG8_BAR; PG8_SCHED;
;             if (full) PG8_LDA(At, 0, 1); PG8_STAGE(PG8_SB(0, 0), b2, voffB); PG8_STAGE(PG8_SB(0, 1), b2 + hstep, voffB); PG8_STAGE(PG8_SA(0, 0), a2, voffA);
.LBB0_521:
	v_add_u32_e32 v0, 0x10000, v225
	ds_read_b128 v[148:151], v0
	ds_read_b128 v[152:155], v0 offset:1024
	ds_read_b128 v[156:159], v0 offset:2048
	ds_read_b128 v[160:163], v0 offset:3072
	v_add_u32_e32 v0, 0x14000, v225
	ds_read_b128 v[132:135], v0
	ds_read_b128 v[136:139], v0 offset:1024
	ds_read_b128 v[140:143], v0 offset:2048
	ds_read_b128 v[144:147], v0 offset:3072
	v_lshl_add_u64 v[2:3], s[34:35], 0, v[204:205]
	s_add_i32 m0, s27, 0xc000
	ds_read_b128 v[176:179], v241
	ds_read_b128 v[192:195], v241 offset:1024
	ds_read_b128 v[172:175], v241 offset:2048
	ds_read_b128 v[188:191], v241 offset:3072
	ds_read_b128 v[168:171], v241 offset:4096
	ds_read_b128 v[184:187], v241 offset:5120
	ds_read_b128 v[164:167], v241 offset:6144
	ds_read_b128 v[180:183], v241 offset:7168
	global_load_lds_dwordx4 v[2:3], off
	v_lshl_add_u64 v[2:3], s[34:35], 0, v[206:207]
	s_add_i32 m0, s27, 0xe000
	s_nop 0
	global_load_lds_dwordx4 v[2:3], off
	s_waitcnt vmcnt(8)
	s_waitcnt lgkmcnt(0)
	s_barrier
	s_setprio 1
	s_waitcnt lgkmcnt(0)
	v_mfma_f32_16x16x32_bf16 v[128:131], v[148:151], v[176:179], v[128:131]
	v_mfma_f32_16x16x32_bf16 v[124:127], v[156:159], v[176:179], v[124:127]
	v_mfma_f32_16x16x32_bf16 v[112:115], v[148:151], v[172:175], v[112:115]
	v_mfma_f32_16x16x32_bf16 v[108:111], v[156:159], v[172:175], v[108:111]
	v_mfma_f32_16x16x32_bf16 v[96:99], v[148:151], v[168:171], v[96:99]
	v_mfma_f32_16x16x32_bf16 v[92:95], v[156:159], v[168:171], v[92:95]
	v_mfma_f32_16x16x32_bf16 v[80:83], v[148:151], v[164:167], v[80:83]
	v_mfma_f32_16x16x32_bf16 v[76:79], v[156:159], v[164:167], v[76:79]
	v_mfma_f32_16x16x32_bf16 v[128:131], v[152:155], v[192:195], v[128:131]
	v_mfma_f32_16x16x32_bf16 v[124:127], v[160:163], v[192:195], v[124:127]
	v_mfma_f32_16x16x32_bf16 v[112:115], v[152:155], v[188:191], v[112:115]
	v_mfma_f32_16x16x32_bf16 v[108:111], v[160:163], v[188:191], v[108:111]
	v_mfma_f32_16x16x32_bf16 v[96:99], v[152:155], v[184:187], v[96:99]
	v_mfma_f32_16x16x32_bf16 v[92:95], v[160:163], v[184:187], v[92:95]
	v_mfma_f32_16x16x32_bf16 v[80:83], v[152:155], v[180:183], v[80:83]
	v_mfma_f32_16x16x32_bf16 v[76:79], v[160:163], v[180:183], v[76:79]
	s_setprio 0
	s_setprio 1
	v_mfma_f32_16x16x32_bf16 v[120:123], v[132:135], v[176:179], v[120:123]
	v_mfma_f32_16x16x32_bf16 v[116:119], v[140:143], v[176:179], v[116:119]
	v_mfma_f32_16x16x32_bf16 v[104:107], v[132:135], v[172:175], v[104:107]
	v_mfma_f32_16x16x32_bf16 v[100:103], v[140:143], v[172:175], v[100:103]
	v_mfma_f32_16x16x32_bf16 v[88:91], v[132:135], v[168:171], v[88:91]
	v_mfma_f32_16x16x32_bf16 v[84:87], v[140:143], v[168:171], v[84:87]
	v_mfma_f32_16x16x32_bf16 v[72:75], v[132:135], v[164:167], v[72:75]
	v_mfma_f32_16x16x32_bf16 v[68:71], v[140:143], v[164:167], v[68:71]
	v_mfma_f32_16x16x32_bf16 v[120:123], v[136:139], v[192:195], v[120:123]
	v_mfma_f32_16x16x32_bf16 v[116:119], v[144:147], v[192:195], v[116:119]
	v_mfma_f32_16x16x32_bf16 v[104:107], v[136:139], v[188:191], v[104:107]
	v_mfma_f32_16x16x32_bf16 v[100:103], v[144:147], v[188:191], v[100:103]
	v_mfma_f32_16x16x32_bf16 v[88:91], v[136:139], v[184:187], v[88:91]
	v_mfma_f32_16x16x32_bf16 v[84:87], v[144:147], v[184:187], v[84:87]
	v_mfma_f32_16x16x32_bf16 v[72:75], v[136:139], v[180:183], v[72:75]
	v_mfma_f32_16x16x32_bf16 v[68:71], v[144:147], v[180:183], v[68:71]
	s_setprio 0
	s_barrier
	v_cndmask_b32_e64 v0, 0, 1, s[30:31]
	v_cmp_ne_u32_e64 s[4:5], 1, v0
	s_andn2_b64 vcc, exec, s[30:31]
	s_cbranch_vccnz .LBB0_523
	ds_read_b128 v[176:179], v241 offset:16384
	ds_read_b128 v[192:195], v241 offset:17408
	ds_read_b128 v[172:175], v241 offset:18432
	ds_read_b128 v[188:191], v241 offset:19456
	ds_read_b128 v[168:171], v241 offset:20480
	ds_read_b128 v[184:187], v241 offset:21504
	ds_read_b128 v[164:167], v241 offset:22528
	ds_read_b128 v[180:183], v241 offset:23552

; #define PG8_STAGE(bufoff, gbase, voff) do { _Pragma("unroll") for (int _i = 0; _i < 2; ++_i) \
;         __builtin_amdgcn_global_load_lds((const unsigned*)((const char*)(gbase) + (voff)[_i]), (PG8_LAS unsigned*)(lds + (bufoff) + ldsw + _i * 8192), 16, 0, 0); } while (0)
; #define PG8_LDA(dst, b, h) do { _Pragma("unroll") for (int m = 0; m < 4; ++m) _Pragma("unroll") for (int k = 0; k < 2; ++k) dst[m][k] = *(const PG8_LAS bf16x8*)(lds + PG8_SA(b, h) + aoff + m * 2048 + k * 1024); } while (0)
; #define PG8_LDB(dst, b, h) do { _Pragma("unroll") for (int n = 0; n < 2; ++n) _Pragma("unroll") for (int k = 0; k < 2; ++k) dst[n][k] = *(const PG8_LAS bf16x8*)(lds + PG8_SB(b, h) + boff + n * 2048 + k * 1024); } while (0)
; #define PG8_MMA(ai, bj, At, Bt) do { __builtin_amdgcn_s_setprio(1); _Pragma("unroll") for (int m = 0; m < 4; ++m) _Pragma("unroll") for (int n = 0; n < 2; ++n) _Pragma("unroll") for (int k = 0; k < 2; ++k) \
;         acc[ai][bj][m][n] = __builtin_amdgcn_mfma_f32_16x16x32_bf16(Bt[n][k], At[m][k], acc[ai][bj][m][n], 0, 0, 0); __builtin_amdgcn_s_setprio(0); } while (0)
; #define PG8_WAIT_V(n) asm volatile("s_waitcnt vmcnt(" #n ")" ::: "memory")
; #define PG8_WAIT_L(n) asm volatile("s_waitcnt lgkmcnt(" #n ")" ::: "memory")
; #define PG8_BAR __builtin_amdgcn_s_barrier()
; #define PG8_SCHED __builtin_amdgcn_sched_barrier(0)
; template <class Epi, class Sched, bool ALIGN_EPI = false, bool SP2 = false>
; __device__ __forceinline__ void gemm_phase(PG8_LAS unsigned char* lds, const Gemm g, const Sched& S, const Epi& E) {
;     ...
;             PG8_LDB(B0, 1, 0); PG8_LDB(B1, 1, 1); PG8_SCHED; PG8_LDA(At, 1, 0); PG8_STAGE(PG8_SA(0, 1), a2 + hstep, voffA);
;             PG8_WAIT_V(8); PG8_WAIT_L(0); PG8_BAR; PG8_MMA(0, 0, At, B0); PG8_MMA(0, 1, At, B1); PG8_BAR; PG8_SCHED;
;             if (full) PG8_LDA(At, 1, 1); PG8_STAGE(PG8_SB(1, 0), b3, voffB); PG8_STAGE(PG8_SB(1, 1), b3 + hstep, voffB); PG8_STAGE(PG8_SA(1, 0), a3, voffA);
.LBB0_525:
	s_barrier
	v_add_u32_e32 v0, 0x18000, v225
	ds_read_b128 v[148:151], v0
	ds_read_b128 v[152:155], v0 offset:1024
	ds_read_b128 v[156:159], v0 offset:2048
	ds_read_b128 v[160:163], v0 offset:3072
	v_add_u32_e32 v0, 0x1c000, v225
	ds_read_b128 v[132:135], v0
	ds_read_b128 v[136:139], v0 offset:1024
	ds_read_b128 v[140:143], v0 offset:2048
	ds_read_b128 v[144:147], v0 offset:3072
	s_add_u32 s38, s38, 0x40000
	s_addc_u32 s39, s39, 0
	s_mov_b32 m0, s58
	v_lshl_add_u64 v[212:213], s[38:39], 0, v[196:197]
	ds_read_b128 v[176:179], v241 offset:32768
	ds_read_b128 v[192:195], v241 offset:33792
	ds_read_b128 v[172:175], v241 offset:34816
	ds_read_b128 v[188:191], v241 offset:35840
	ds_read_b128 v[168:171], v241 offset:36864
	ds_read_b128 v[184:187], v241 offset:37888
	ds_read_b128 v[164:167], v241 offset:38912
	ds_read_b128 v[180:183], v241 offset:39936
	global_load_lds_dwordx4 v[212:213], off
	v_lshl_add_u64 v[212:213], s[38:39], 0, v[200:201]
	s_mov_b32 m0, s59
	s_nop 0
	global_load_lds_dwordx4 v[212:213], off
	s_waitcnt vmcnt(8)
	s_waitcnt lgkmcnt(0)
	s_barrier
	s_setprio 1
	s_waitcnt lgkmcnt(0)
	v_mfma_f32_16x16x32_bf16 v[128:131], v[148:151], v[176:179], v[128:131]
	v_mfma_f32_16x16x32_bf16 v[124:127], v[156:159], v[176:179], v[124:127]
	v_mfma_f32_16x16x32_bf16 v[112:115], v[148:151], v[172:175], v[112:115]
	v_mfma_f32_16x16x32_bf16 v[108:111], v[156:159], v[172:175], v[108:111]
	v_mfma_f32_16x16x32_bf16 v[96:99], v[148:151], v[168:171], v[96:99]
	v_mfma_f32_16x16x32_bf16 v[92:95], v[156:159], v[168:171], v[92:95]
	v_mfma_f32_16x16x32_bf16 v[80:83], v[148:151], v[164:167], v[80:83]
	v_mfma_f32_16x16x32_bf16 v[76:79], v[156:159], v[164:167], v[76:79]
	v_mfma_f32_16x16x32_bf16 v[128:131], v[152:155], v[192:195], v[128:131]
	v_mfma_f32_16x16x32_bf16 v[124:127], v[160:163], v[192:195], v[124:127]
	v_mfma_f32_16x16x32_bf16 v[112:115], v[152:155], v[188:191], v[112:115]
	v_mfma_f32_16x16x32_bf16 v[108:111], v[160:163], v[188:191], v[108:111]
	v_mfma_f32_16x16x32_bf16 v[96:99], v[152:155], v[184:187], v[96:99]
	v_mfma_f32_16x16x32_bf16 v[92:95], v[160:163], v[184:187], v[92:95]
	v_mfma_f32_16x16x32_bf16 v[80:83], v[152:155], v[180:183], v[80:83]
	v_mfma_f32_16x16x32_bf16 v[76:79], v[160:163], v[180:183], v[76:79]
	s_setprio 0
	s_setprio 1
	v_mfma_f32_16x16x32_bf16 v[120:123], v[132:135], v[176:179], v[120:123]
	v_mfma_f32_16x16x32_bf16 v[116:119], v[140:143], v[176:179], v[116:119]
	v_mfma_f32_16x16x32_bf16 v[104:107], v[132:135], v[172:175], v[104:107]
	v_mfma_f32_16x16x32_bf16 v[100:103], v[140:143], v[172:175], v[100:103]
	v_mfma_f32_16x16x32_bf16 v[88:91], v[132:135], v[168:171], v[88:91]
	v_mfma_f32_16x16x32_bf16 v[84:87], v[140:143], v[168:171], v[84:87]
	v_mfma_f32_16x16x32_bf16 v[72:75], v[132:135], v[164:167], v[72:75]
	v_mfma_f32_16x16x32_bf16 v[68:71], v[140:143], v[164:167], v[68:71]
	v_mfma_f32_16x16x32_bf16 v[120:123], v[136:139], v[192:195], v[120:123]
	v_mfma_f32_16x16x32_bf16 v[116:119], v[144:147], v[192:195], v[116:119]
	v_mfma_f32_16x16x32_bf16 v[104:107], v[136:139], v[188:191], v[104:107]
	v_mfma_f32_16x16x32_bf16 v[100:103], v[144:147], v[188:191], v[100:103]
	v_mfma_f32_16x16x32_bf16 v[88:91], v[136:139], v[184:187], v[88:91]
	v_mfma_f32_16x16x32_bf16 v[84:87], v[144:147], v[184:187], v[84:87]
	v_mfma_f32_16x16x32_bf16 v[72:75], v[136:139], v[180:183], v[72:75]
	v_mfma_f32_16x16x32_bf16 v[68:71], v[144:147], v[180:183], v[68:71]
	s_setprio 0
	s_barrier
	s_and_b64 vcc, exec, s[4:5]
	s_cbranch_vccnz .LBB0_527
	ds_read_b128 v[176:179], v241 offset:49152
	ds_read_b128 v[192:195], v241 offset:50176
	ds_read_b128 v[172:175], v241 offset:51200
	ds_read_b128 v[188:191], v241 offset:52224
	ds_read_b128 v[168:171], v241 offset:53248
	ds_read_b128 v[184:187], v241 offset:54272
	ds_read_b128 v[164:167], v241 offset:55296
	ds_read_b128 v[180:183], v241 offset:56320

; template<int MODE,int THRL> __device__ __forceinline__ void attn_unit(int b,int h,int qb,const bf16*Q,const bf16*__restrict__ K,const bf16*__restrict__ V,bf16*O,char*shm,const float*aux0,const float*aux1,const float*aux2){
;     ...
;     if(wid==0){ const float a=aux1[(b*128+lane)*32+h], c=aux1[(b*128+64+lane)*32+h]; float sa=a, sc=c;
;       #pragma unroll
;       for(int o=1;o<64;o<<=1){ const float ta=__shfl_up(sa,o), tc=__shfl_up(sc,o); if(lane>=o){sa+=ta;sc+=tc;} }
;       const float tot=__shfl(sa,63); bp0[lane]=sa-a; bp0[64+lane]=tot+sc-c; }
;     asm volatile("s_waitcnt vmcnt(0) lgkmcnt(0)\n\ts_barrier":::"memory");
;     const float*cum0=aux0+(long)(b*NHEAD+h)*SEQ; const int ntp=q0/KVBLK;
;     float gq=fabsf(aux2[128+lane]), gk=fabsf(aux2[192+lane]);
;     #pragma unroll
;     for(int o=1;o<64;o<<=1){ gq=fmaxf(gq,__shfl_xor(gq,o)); gk=fmaxf(gk,__shfl_xor(gk,o)); }
;     const float thr=-(cum0[q0]+bp0[q0>>6])*LOG2E-(2.02f*8.f*LOG2E*gq*gk+38.f);
;     bool c0=false,c1=false;
;     if(lane<ntp) c0=(-(cum0[64*lane+63]+bp0[lane])*LOG2E<thr);
;     if(lane+64<ntp) c1=(-(cum0[64*(lane+64)+63]+bp0[lane+64])*LOG2E<thr);
; __global__ void __launch_bounds__(NWAVES * 64, 2) mk_fwd(Args) {
;     ...
;                         for (int i = 0; i < 2; ++i) { const int h = __builtin_amdgcn_readfirstlane(hmap[i ? 7 - r : r]);
.LBB0_726:
	s_and_b64 s[4:5], s[8:9], exec
	s_cselect_b32 s1, s88, s64
	s_lshl_b32 s1, s1, 2
	s_add_i32 s1, s1, 0
	s_add_i32 s1, s1, 0x20120
	v_mov_b32_e32 v0, s1
	ds_read_b32 v0, v0
	v_mov_b32_e32 v52, v219
	s_load_dwordx2 s[6:7], s[96:97], 0x48
	s_waitcnt lgkmcnt(0)
	s_waitcnt lgkmcnt(0)
	v_readfirstlane_b32 s1, v0
	v_and_b32_e32 v217, 63, v52
	v_readfirstlane_b32 s44, v52
	v_readlane_b32 s22, v255, 26
	v_readlane_b32 s23, v255, 27
	s_add_i32 s24, s1, s72
	s_ashr_i32 s25, s24, 31
	s_lshl_b64 s[22:23], s[22:23], 2
	s_lshl_b64 s[24:25], s[24:25], 15
	s_add_u32 s22, s6, s22
	s_addc_u32 s23, s7, s23
	s_add_u32 s24, s42, s24
	s_addc_u32 s25, s82, s25
	s_and_b64 s[26:27], s[8:9], exec
	s_cselect_b32 s26, s76, s83
	s_lshl_b32 s27, s26, 10
	v_lshlrev_b32_e32 v100, 2, v217
	v_mov_b32_e32 v103, s27
	v_lshlrev_b32_e32 v105, 8, v217
	v_or_b32_e32 v107, 64, v217
	v_lshlrev_b32_e32 v107, 8, v107
	global_load_dword v101, v100, s[22:23] offset:512
	global_load_dword v102, v100, s[22:23] offset:768
	global_load_dword v104, v103, s[24:25]
	global_load_dword v106, v105, s[24:25] offset:252
	global_load_dword v108, v107, s[24:25] offset:252
	s_cmp_gt_u32 s44, 63
	v_cmp_gt_u32_e32 vcc, 32, v217
	v_lshl_add_u32 v0, v217, 2, 0
	s_cbranch_scc1 .LBB0_728
	v_lshl_or_b32 v2, v217, 5, s65
	v_add_u32_e32 v2, s1, v2
	v_ashrrev_i32_e32 v3, 31, v2
	v_lshl_add_u64 v[4:5], v[2:3], 2, s[60:61]
	v_add_u32_e32 v2, 0x800, v2
	v_ashrrev_i32_e32 v3, 31, v2
	v_lshl_add_u64 v[2:3], v[2:3], 2, s[60:61]
	global_load_dword v4, v[4:5], off
	v_add_u32_e32 v7, -2, v240
	global_load_dword v2, v[2:3], off
	v_and_b32_e32 v3, 64, v240
	v_add_u32_e32 v5, -1, v240
	v_cmp_lt_i32_e64 s[4:5], v5, v3
	s_nop 1
	v_cndmask_b32_e64 v5, v5, v240, s[4:5]
	v_lshlrev_b32_e32 v5, 2, v5
	v_cmp_eq_u32_e64 s[4:5], 0, v217
	s_waitcnt vmcnt(1)
	ds_bpermute_b32 v6, v5, v4
	s_waitcnt vmcnt(0)
	ds_bpermute_b32 v5, v5, v2
	s_waitcnt lgkmcnt(1)
	v_add_f32_e32 v6, v4, v6
	v_cndmask_b32_e64 v6, v6, v4, s[4:5]
	s_waitcnt lgkmcnt(0)
	v_add_f32_e32 v5, v2, v5
	v_cndmask_b32_e64 v5, v5, v2, s[4:5]
	v_cmp_lt_i32_e64 s[4:5], v7, v3
	s_nop 1
	v_cndmask_b32_e64 v7, v7, v240, s[4:5]
	v_lshlrev_b32_e32 v7, 2, v7
	ds_bpermute_b32 v8, v7, v6
	ds_bpermute_b32 v7, v7, v5
	v_cmp_gt_u32_e64 s[4:5], 2, v217
	s_waitcnt lgkmcnt(1)
	v_add_f32_e32 v8, v6, v8
	s_waitcnt lgkmcnt(0)
	v_add_f32_e32 v7, v5, v7
	v_cndmask_b32_e64 v5, v7, v5, s[4:5]
	v_add_u32_e32 v7, -4, v240
	v_cndmask_b32_e64 v6, v8, v6, s[4:5]
	v_cmp_lt_i32_e64 s[4:5], v7, v3
	s_nop 1
	v_cndmask_b32_e64 v7, v7, v240, s[4:5]
	v_lshlrev_b32_e32 v7, 2, v7
	ds_bpermute_b32 v8, v7, v6
	ds_bpermute_b32 v7, v7, v5
	v_cmp_gt_u32_e64 s[4:5], 4, v217
	s_waitcnt lgkmcnt(1)
	v_add_f32_e32 v8, v6, v8
	s_waitcnt lgkmcnt(0)
	v_add_f32_e32 v7, v5, v7
	v_cndmask_b32_e64 v5, v7, v5, s[4:5]
	v_add_u32_e32 v7, -8, v240
	v_cndmask_b32_e64 v6, v8, v6, s[4:5]
	v_cmp_lt_i32_e64 s[4:5], v7, v3
	s_nop 1
	v_cndmask_b32_e64 v7, v7, v240, s[4:5]
	v_lshlrev_b32_e32 v7, 2, v7
	ds_bpermute_b32 v8, v7, v6
	ds_bpermute_b32 v7, v7, v5
	v_cmp_gt_u32_e64 s[4:5], 8, v217
	s_waitcnt lgkmcnt(1)
	v_add_f32_e32 v8, v6, v8
	s_waitcnt lgkmcnt(0)
	v_add_f32_e32 v7, v5, v7
	v_cndmask_b32_e64 v5, v7, v5, s[4:5]
	v_add_u32_e32 v7, -16, v240
	v_cndmask_b32_e64 v6, v8, v6, s[4:5]
	v_cmp_lt_i32_e64 s[4:5], v7, v3
	s_nop 1
	v_cndmask_b32_e64 v7, v7, v240, s[4:5]
	v_lshlrev_b32_e32 v7, 2, v7
	ds_bpermute_b32 v8, v7, v6
	ds_bpermute_b32 v7, v7, v5
	v_cmp_gt_u32_e64 s[4:5], 16, v217
	s_waitcnt lgkmcnt(1)
	v_add_f32_e32 v8, v6, v8
	s_waitcnt lgkmcnt(0)
	v_add_f32_e32 v7, v5, v7
	v_cndmask_b32_e64 v5, v7, v5, s[4:5]
	v_subrev_u32_e32 v7, 32, v240
	v_cndmask_b32_e64 v6, v8, v6, s[4:5]
	v_cmp_lt_i32_e64 s[4:5], v7, v3
	s_nop 1
	v_cndmask_b32_e64 v3, v7, v240, s[4:5]
	v_lshlrev_b32_e32 v3, 2, v3
	ds_bpermute_b32 v7, v3, v6
	ds_bpermute_b32 v3, v3, v5
	s_waitcnt lgkmcnt(1)
	v_add_f32_e32 v7, v6, v7
	s_waitcnt lgkmcnt(0)
	v_add_f32_e32 v3, v5, v3
	v_cndmask_b32_e32 v3, v3, v5, vcc
	v_cndmask_b32_e32 v5, v7, v6, vcc
	v_bfrev_b32_e32 v6, 0.5
	v_lshl_or_b32 v6, v240, 2, v6
	ds_bpermute_b32 v6, v6, v5
	v_sub_f32_e32 v4, v5, v4
	v_add_u32_e32 v5, 0x1d000, v0
	s_waitcnt lgkmcnt(0)
	v_add_f32_e32 v3, v3, v6
	v_sub_f32_e32 v2, v3, v2
	ds_write2st64_b32 v5, v4, v2 offset1:1
; template<int MODE,int THRL> __device__ __forceinline__ void attn_unit(int b,int h,int qb,const bf16*Q,const bf16*__restrict__ K,const bf16*__restrict__ V,bf16*O,char*shm,const float*aux0,const float*aux1,const float*aux2){
;     ...
;     asm volatile("s_waitcnt vmcnt(0) lgkmcnt(0)\n\ts_barrier":::"memory");
;     const float*cum0=aux0+(long)(b*NHEAD+h)*SEQ; const int ntp=q0/KVBLK;
;     float gq=fabsf(aux2[128+lane]), gk=fabsf(aux2[192+lane]);
;     #pragma unroll
;     for(int o=1;o<64;o<<=1){ gq=fmaxf(gq,__shfl_xor(gq,o)); gk=fmaxf(gk,__shfl_xor(gk,o)); }
;     const float thr=-(cum0[q0]+bp0[q0>>6])*LOG2E-(2.02f*8.f*LOG2E*gq*gk+38.f);
;     bool c0=false,c1=false;
;     if(lane<ntp) c0=(-(cum0[64*lane+63]+bp0[lane])*LOG2E<thr);
;     if(lane+64<ntp) c1=(-(cum0[64*(lane+64)+63]+bp0[lane+64])*LOG2E<thr);
;     const int cnt=__popcll(__ballot(c0))+__popcll(__ballot(c1));
.LBB0_728:
	v_readlane_b32 s2, v255, 26
	s_and_b64 s[4:5], s[8:9], exec
	v_readlane_b32 s3, v255, 27
	s_cselect_b32 s16, s76, s83
	s_lshl_b64 s[4:5], s[2:3], 2
	s_add_u32 s10, s6, s4
	s_addc_u32 s11, s7, s5
	s_waitcnt vmcnt(0) lgkmcnt(0)
	s_barrier
	v_lshlrev_b32_e32 v2, 2, v217
	v_mov_b32_e32 v3, v101
	v_and_b32_e32 v6, 64, v240
	v_mov_b32_e32 v2, v102
	v_add_u32_e32 v6, 64, v6
	v_xor_b32_e32 v7, 1, v240
	v_cmp_lt_i32_e32 vcc, v7, v6
	s_add_i32 s4, s1, s72
	s_ashr_i32 s5, s4, 31
	v_cndmask_b32_e32 v7, v240, v7, vcc
	v_lshlrev_b32_e32 v7, 2, v7
	s_lshl_b64 s[4:5], s[4:5], 15
	s_add_u32 s6, s42, s4
	s_addc_u32 s7, s82, s5
	s_lshl_b32 s10, s16, 10
	s_lshl_b32 s56, s16, 2
	s_mov_b32 s2, 0xbfb8aa3b
	s_mov_b64 s[12:13], 0
	s_waitcnt vmcnt(1)
	v_and_b32_e32 v4, 0x7fffffff, v3
	ds_bpermute_b32 v4, v7, v4
	s_waitcnt vmcnt(0)
	v_and_b32_e32 v5, 0x7fffffff, v2
	v_max_f32_e64 v3, |v3|, |v3|
	v_max_f32_e64 v2, |v2|, |v2|
	s_waitcnt lgkmcnt(0)
	v_max_f32_e32 v4, v4, v4
	v_max_f32_e32 v3, v3, v4
	ds_bpermute_b32 v4, v7, v5
	s_waitcnt lgkmcnt(0)
	v_max_f32_e32 v4, v4, v4
	v_max_f32_e32 v2, v2, v4
	v_xor_b32_e32 v4, 2, v240
	v_cmp_lt_i32_e32 vcc, v4, v6
	s_nop 1
	v_cndmask_b32_e32 v4, v240, v4, vcc
	v_lshlrev_b32_e32 v4, 2, v4
	ds_bpermute_b32 v5, v4, v3
	ds_bpermute_b32 v4, v4, v2
	s_waitcnt lgkmcnt(1)
	v_max_f32_e32 v5, v5, v5
	s_waitcnt lgkmcnt(0)
	v_max_f32_e32 v4, v4, v4
	v_max_f32_e32 v2, v2, v4
	v_xor_b32_e32 v4, 4, v240
	v_cmp_lt_i32_e32 vcc, v4, v6
	v_max_f32_e32 v3, v3, v5
	s_nop 0
	v_cndmask_b32_e32 v4, v240, v4, vcc
	v_lshlrev_b32_e32 v4, 2, v4
	ds_bpermute_b32 v5, v4, v3
	ds_bpermute_b32 v4, v4, v2
	s_waitcnt lgkmcnt(1)
	v_max_f32_e32 v5, v5, v5
	s_waitcnt lgkmcnt(0)
	v_max_f32_e32 v4, v4, v4
	v_max_f32_e32 v2, v2, v4
	v_xor_b32_e32 v4, 8, v240
	v_cmp_lt_i32_e32 vcc, v4, v6
	v_max_f32_e32 v3, v3, v5
	s_nop 0
	v_cndmask_b32_e32 v4, v240, v4, vcc
	v_lshlrev_b32_e32 v4, 2, v4
	ds_bpermute_b32 v5, v4, v3
	ds_bpermute_b32 v4, v4, v2
	s_waitcnt lgkmcnt(1)
	v_max_f32_e32 v5, v5, v5
	s_waitcnt lgkmcnt(0)
	v_max_f32_e32 v4, v4, v4
	v_max_f32_e32 v2, v2, v4
	v_xor_b32_e32 v4, 16, v240
	v_cmp_lt_i32_e32 vcc, v4, v6
	v_max_f32_e32 v3, v3, v5
	s_nop 0
	v_cndmask_b32_e32 v4, v240, v4, vcc
	v_lshlrev_b32_e32 v4, 2, v4
	ds_bpermute_b32 v5, v4, v3
	ds_bpermute_b32 v4, v4, v2
	s_waitcnt lgkmcnt(1)
	v_max_f32_e32 v5, v5, v5
	s_waitcnt lgkmcnt(0)
	v_max_f32_e32 v4, v4, v4
	v_max_f32_e32 v2, v2, v4
	v_xor_b32_e32 v4, 32, v240
	v_cmp_lt_i32_e32 vcc, v4, v6
	v_max_f32_e32 v3, v3, v5
	s_nop 0
	v_cndmask_b32_e32 v4, v240, v4, vcc
	v_lshlrev_b32_e32 v4, 2, v4
	ds_bpermute_b32 v5, v4, v3
	ds_bpermute_b32 v4, v4, v2
	v_cmp_gt_u32_e32 vcc, s56, v217
	s_waitcnt lgkmcnt(1)
	v_max_f32_e32 v5, v5, v5
	s_waitcnt lgkmcnt(0)
	v_max_f32_e32 v4, v4, v4
	v_max_f32_e32 v2, v2, v4
	v_mov_b32_e32 v4, s10
	v_mov_b32_e32 v4, v104
	s_lshl_b32 s10, s16, 4
	s_add_i32 s10, s10, 0
	s_add_i32 s10, s10, 0x1d000
	v_max_f32_e32 v3, v3, v5
	v_mov_b32_e32 v5, s10
	ds_read_b32 v5, v5
	v_mul_f32_e32 v3, 0x41ba82f9, v3
	v_fmaak_f32 v2, v2, v3, 0x42180000
	s_mov_b64 s[10:11], 0
	s_waitcnt vmcnt(0) lgkmcnt(0)
	v_add_f32_e32 v4, v4, v5
	v_fma_f32 v2, v4, s2, -v2
	s_and_saveexec_b64 s[14:15], vcc
	s_cbranch_execz .LBB0_730
	v_lshlrev_b32_e32 v3, 8, v217
	v_mov_b32_e32 v3, v106
	v_add_u32_e32 v0, 0x1d000, v0
	ds_read_b32 v0, v0
	s_waitcnt vmcnt(0) lgkmcnt(0)
	v_add_f32_e32 v0, v3, v0
	v_mul_f32_e32 v0, 0xbfb8aa3b, v0
	v_cmp_lt_f32_e32 vcc, v0, v2
	s_and_b64 s[12:13], vcc, exec
.LBB0_730:
	s_or_b64 exec, exec, s[14:15]
	v_or_b32_e32 v0, 64, v217
	v_cmp_gt_u32_e32 vcc, s56, v0
	s_and_saveexec_b64 s[14:15], vcc
	s_cbranch_execz .LBB0_732
	v_lshlrev_b32_e32 v3, 8, v0
	v_mov_b32_e32 v3, v108
	v_lshl_add_u32 v0, v0, 2, 0
	v_add_u32_e32 v0, 0x1d000, v0
	ds_read_b32 v0, v0
	s_waitcnt vmcnt(0) lgkmcnt(0)
	v_add_f32_e32 v0, v3, v0
	v_mul_f32_e32 v0, 0xbfb8aa3b, v0
	v_cmp_lt_f32_e32 vcc, v0, v2
	s_and_b64 s[10:11], vcc, exec
